# EpiResid epilogue hand-written: two column groups of X/mod loads in flight, later groups issued as their landing registers free up (were four load-wait-store rounds)
# baseline (speedup 1.0000x reference)
.LBB0_1206:
	s_movk_i32 s82, 0x4800
	s_movk_i32 s83, 0x1000
	s_mov_b32 s86, 0x3a800000
	s_mov_b64 s[84:85], s[48:49]
	s_mov_b64 s[30:31], -1
	s_mov_b64 s[6:7], 0
	s_cmp_lt_i32 s80, 1
	s_mov_b64 s[8:9], 0
	s_cbranch_scc1 .LBB0_1214
	s_cmp_gt_i32 s80, 1
	s_cbranch_scc0 .LBB0_1211
	s_cmp_eq_u32 s80, 2
	s_mov_b64 s[8:9], -1
	s_cbranch_scc0 .LBB0_1210
	s_lshr_b32 s0, s53, 3
	s_cmp_lt_i32 s53, 64
	s_mulk_i32 s0, 0x2400
	s_cselect_b32 s8, s0, 0x12000
	s_ashr_i32 s9, s8, 31
	s_lshl_b64 s[8:9], s[8:9], 2
	v_readlane_b32 s0, v255, 29
	v_or_b32_e32 v0, s52, v146
	s_add_u32 s8, s0, s8
	v_readlane_b32 s0, v255, 30
	v_lshlrev_b32_e32 v160, 2, v0
	v_add_u32_e32 v2, s5, v236
	s_addc_u32 s9, s0, s9
	v_lshl_add_u32 v152, v2, 12, v160
	v_add_u32_e32 v3, 0x10, v2
	v_lshl_add_u32 v153, v3, 12, v160
	v_add_u32_e32 v3, 0x20, v2
	v_lshl_add_u32 v154, v3, 12, v160
	v_add_u32_e32 v3, 0x30, v2
	v_lshl_add_u32 v155, v3, 12, v160
	v_add_u32_e32 v3, 0x80, v2
	v_lshl_add_u32 v156, v3, 12, v160
	v_add_u32_e32 v3, 0x90, v2
	v_lshl_add_u32 v157, v3, 12, v160
	v_add_u32_e32 v3, 0xa0, v2
	v_lshl_add_u32 v158, v3, 12, v160
	v_add_u32_e32 v3, 0xb0, v2
	v_lshl_add_u32 v159, v3, 12, v160
	global_load_dwordx4 v[162:165], v160, s[8:9]
	global_load_dwordx4 v[166:169], v152, s[12:13]
	global_load_dwordx4 v[170:173], v153, s[12:13]
	global_load_dwordx4 v[174:177], v154, s[12:13]
	global_load_dwordx4 v[178:181], v155, s[12:13]
	global_load_dwordx4 v[182:185], v156, s[12:13]
	global_load_dwordx4 v[186:189], v157, s[12:13]
	global_load_dwordx4 v[190:193], v158, s[12:13]
	global_load_dwordx4 v[194:197], v159, s[12:13]
	global_load_dwordx4 v[248:251], v160, s[8:9] offset:64
	global_load_dwordx4 v[198:201], v152, s[12:13] offset:64
	global_load_dwordx4 v[202:205], v153, s[12:13] offset:64
	global_load_dwordx4 v[206:209], v154, s[12:13] offset:64
	global_load_dwordx4 v[210:213], v155, s[12:13] offset:64
	global_load_dwordx4 v[224:227], v156, s[12:13] offset:64
	global_load_dwordx4 v[228:231], v157, s[12:13] offset:64
	global_load_dwordx4 v[132:135], v158, s[12:13] offset:64
	global_load_dwordx4 v[136:139], v159, s[12:13] offset:64
	s_waitcnt vmcnt(9)
	v_pk_mul_f32 v[162:163], s[44:45], v[162:163]
	v_pk_mul_f32 v[164:165], s[44:45], v[164:165]
	v_pk_fma_f32 v[166:167], v[128:129], v[162:163], v[166:167]
	v_pk_fma_f32 v[168:169], v[130:131], v[164:165], v[168:169]
	global_store_dwordx4 v152, v[166:169], s[12:13]
	v_pk_fma_f32 v[170:171], v[112:113], v[162:163], v[170:171]
	v_pk_fma_f32 v[172:173], v[114:115], v[164:165], v[172:173]
	global_store_dwordx4 v153, v[170:173], s[12:13]
	v_pk_fma_f32 v[174:175], v[96:97], v[162:163], v[174:175]
	v_pk_fma_f32 v[176:177], v[98:99], v[164:165], v[176:177]
	global_store_dwordx4 v154, v[174:177], s[12:13]
	v_pk_fma_f32 v[178:179], v[80:81], v[162:163], v[178:179]
	v_pk_fma_f32 v[180:181], v[82:83], v[164:165], v[180:181]
	global_store_dwordx4 v155, v[178:181], s[12:13]
	v_pk_fma_f32 v[182:183], v[64:65], v[162:163], v[182:183]
	v_pk_fma_f32 v[184:185], v[66:67], v[164:165], v[184:185]
	global_store_dwordx4 v156, v[182:185], s[12:13]
	v_pk_fma_f32 v[186:187], v[48:49], v[162:163], v[186:187]
	v_pk_fma_f32 v[188:189], v[50:51], v[164:165], v[188:189]
	global_store_dwordx4 v157, v[186:189], s[12:13]
	v_pk_fma_f32 v[190:191], v[32:33], v[162:163], v[190:191]
	v_pk_fma_f32 v[192:193], v[34:35], v[164:165], v[192:193]
	global_store_dwordx4 v158, v[190:193], s[12:13]
	v_pk_fma_f32 v[194:195], v[16:17], v[162:163], v[194:195]
	v_pk_fma_f32 v[196:197], v[18:19], v[164:165], v[196:197]
	global_store_dwordx4 v159, v[194:197], s[12:13]
	global_load_dwordx4 v[162:165], v160, s[8:9] offset:512
	global_load_dwordx4 v[166:169], v152, s[12:13] offset:512
	global_load_dwordx4 v[170:173], v153, s[12:13] offset:512
	global_load_dwordx4 v[174:177], v154, s[12:13] offset:512
	global_load_dwordx4 v[178:181], v155, s[12:13] offset:512
	global_load_dwordx4 v[182:185], v156, s[12:13] offset:512
	global_load_dwordx4 v[186:189], v157, s[12:13] offset:512
	global_load_dwordx4 v[190:193], v158, s[12:13] offset:512
	global_load_dwordx4 v[194:197], v159, s[12:13] offset:512
	s_waitcnt vmcnt(17)
	v_pk_mul_f32 v[248:249], s[44:45], v[248:249]
	v_pk_mul_f32 v[250:251], s[44:45], v[250:251]
	v_pk_fma_f32 v[198:199], v[124:125], v[248:249], v[198:199]
	v_pk_fma_f32 v[200:201], v[126:127], v[250:251], v[200:201]
	global_store_dwordx4 v152, v[198:201], s[12:13] offset:64
	v_pk_fma_f32 v[202:203], v[108:109], v[248:249], v[202:203]
	v_pk_fma_f32 v[204:205], v[110:111], v[250:251], v[204:205]
	global_store_dwordx4 v153, v[202:205], s[12:13] offset:64
	v_pk_fma_f32 v[206:207], v[92:93], v[248:249], v[206:207]
	v_pk_fma_f32 v[208:209], v[94:95], v[250:251], v[208:209]
	global_store_dwordx4 v154, v[206:209], s[12:13] offset:64
	v_pk_fma_f32 v[210:211], v[76:77], v[248:249], v[210:211]
	v_pk_fma_f32 v[212:213], v[78:79], v[250:251], v[212:213]
	global_store_dwordx4 v155, v[210:213], s[12:13] offset:64
	v_pk_fma_f32 v[224:225], v[60:61], v[248:249], v[224:225]
	v_pk_fma_f32 v[226:227], v[62:63], v[250:251], v[226:227]
	global_store_dwordx4 v156, v[224:227], s[12:13] offset:64
	v_pk_fma_f32 v[228:229], v[44:45], v[248:249], v[228:229]
	v_pk_fma_f32 v[230:231], v[46:47], v[250:251], v[230:231]
	global_store_dwordx4 v157, v[228:231], s[12:13] offset:64
	v_pk_fma_f32 v[132:133], v[28:29], v[248:249], v[132:133]
	v_pk_fma_f32 v[134:135], v[30:31], v[250:251], v[134:135]
	global_store_dwordx4 v158, v[132:135], s[12:13] offset:64
	v_pk_fma_f32 v[136:137], v[12:13], v[248:249], v[136:137]
	v_pk_fma_f32 v[138:139], v[14:15], v[250:251], v[138:139]
	global_store_dwordx4 v159, v[136:139], s[12:13] offset:64
	global_load_dwordx4 v[248:251], v160, s[8:9] offset:576
	global_load_dwordx4 v[198:201], v152, s[12:13] offset:576
	global_load_dwordx4 v[202:205], v153, s[12:13] offset:576
	global_load_dwordx4 v[206:209], v154, s[12:13] offset:576
	global_load_dwordx4 v[210:213], v155, s[12:13] offset:576
	global_load_dwordx4 v[224:227], v156, s[12:13] offset:576
	global_load_dwordx4 v[228:231], v157, s[12:13] offset:576
	global_load_dwordx4 v[132:135], v158, s[12:13] offset:576
	global_load_dwordx4 v[136:139], v159, s[12:13] offset:576
	s_waitcnt vmcnt(17)
	v_pk_mul_f32 v[162:163], s[44:45], v[162:163]
	v_pk_mul_f32 v[164:165], s[44:45], v[164:165]
	v_pk_fma_f32 v[166:167], v[120:121], v[162:163], v[166:167]
	v_pk_fma_f32 v[168:169], v[122:123], v[164:165], v[168:169]
	global_store_dwordx4 v152, v[166:169], s[12:13] offset:512
	v_pk_fma_f32 v[170:171], v[104:105], v[162:163], v[170:171]
	v_pk_fma_f32 v[172:173], v[106:107], v[164:165], v[172:173]
	global_store_dwordx4 v153, v[170:173], s[12:13] offset:512
	v_pk_fma_f32 v[174:175], v[88:89], v[162:163], v[174:175]
	v_pk_fma_f32 v[176:177], v[90:91], v[164:165], v[176:177]
	global_store_dwordx4 v154, v[174:177], s[12:13] offset:512
	v_pk_fma_f32 v[178:179], v[72:73], v[162:163], v[178:179]
	v_pk_fma_f32 v[180:181], v[74:75], v[164:165], v[180:181]
	global_store_dwordx4 v155, v[178:181], s[12:13] offset:512
	v_pk_fma_f32 v[182:183], v[56:57], v[162:163], v[182:183]
	v_pk_fma_f32 v[184:185], v[58:59], v[164:165], v[184:185]
	global_store_dwordx4 v156, v[182:185], s[12:13] offset:512
	v_pk_fma_f32 v[186:187], v[40:41], v[162:163], v[186:187]
	v_pk_fma_f32 v[188:189], v[42:43], v[164:165], v[188:189]
	global_store_dwordx4 v157, v[186:189], s[12:13] offset:512
	v_pk_fma_f32 v[190:191], v[24:25], v[162:163], v[190:191]
	v_pk_fma_f32 v[192:193], v[26:27], v[164:165], v[192:193]
	global_store_dwordx4 v158, v[190:193], s[12:13] offset:512
	v_pk_fma_f32 v[194:195], v[8:9], v[162:163], v[194:195]
	v_pk_fma_f32 v[196:197], v[10:11], v[164:165], v[196:197]
	global_store_dwordx4 v159, v[194:197], s[12:13] offset:512
	s_waitcnt vmcnt(8)
	v_pk_mul_f32 v[248:249], s[44:45], v[248:249]
	v_pk_mul_f32 v[250:251], s[44:45], v[250:251]
	v_pk_fma_f32 v[198:199], v[116:117], v[248:249], v[198:199]
	v_pk_fma_f32 v[200:201], v[118:119], v[250:251], v[200:201]
	global_store_dwordx4 v152, v[198:201], s[12:13] offset:576
	v_pk_fma_f32 v[202:203], v[100:101], v[248:249], v[202:203]
	v_pk_fma_f32 v[204:205], v[102:103], v[250:251], v[204:205]
	global_store_dwordx4 v153, v[202:205], s[12:13] offset:576
	v_pk_fma_f32 v[206:207], v[84:85], v[248:249], v[206:207]
	v_pk_fma_f32 v[208:209], v[86:87], v[250:251], v[208:209]
	global_store_dwordx4 v154, v[206:209], s[12:13] offset:576
	v_pk_fma_f32 v[210:211], v[68:69], v[248:249], v[210:211]
	v_pk_fma_f32 v[212:213], v[70:71], v[250:251], v[212:213]
	global_store_dwordx4 v155, v[210:213], s[12:13] offset:576
	v_pk_fma_f32 v[224:225], v[52:53], v[248:249], v[224:225]
	v_pk_fma_f32 v[226:227], v[54:55], v[250:251], v[226:227]
	global_store_dwordx4 v156, v[224:227], s[12:13] offset:576
	v_pk_fma_f32 v[228:229], v[36:37], v[248:249], v[228:229]
	v_pk_fma_f32 v[230:231], v[38:39], v[250:251], v[230:231]
	global_store_dwordx4 v157, v[228:231], s[12:13] offset:576
	v_pk_fma_f32 v[132:133], v[20:21], v[248:249], v[132:133]
	v_pk_fma_f32 v[134:135], v[22:23], v[250:251], v[134:135]
	global_store_dwordx4 v158, v[132:135], s[12:13] offset:576
	v_pk_fma_f32 v[136:137], v[4:5], v[248:249], v[136:137]
	v_pk_fma_f32 v[138:139], v[6:7], v[250:251], v[138:139]
	global_store_dwordx4 v159, v[136:139], s[12:13] offset:576
	s_ashr_i32 s53, s52, 31
	s_mov_b64 s[8:9], 0
